# v10 plus wait-state fix (s_nop between v_cmp and v_cndmask in A epilogue) and hoisted bpermute index in A chunk loop
# speedup vs baseline: 1.0192x; 1.0072x over previous
; #define LAS3 __attribute__((address_space(3)))
; template <int MODE>
; DI void attn_seq(const Params& p, int layer, char* smem, const int tid, const int nitems, bf16_t* ob, const int ostride) {
;     ...
;   const int jl = layer >> 1;
;   const int lane = tid & 63, wv = __builtin_amdgcn_readfirstlane(tid >> 6), r = lane & 31, h = lane >> 5;
;   const int item0 = (int)(((long)blockIdx.x * nitems) / (long)gridDim.x);
;   const int nit = (int)(((long)(blockIdx.x + 1) * nitems) / (long)gridDim.x) - item0;
;   if (nit <= 0) return;
;   LAS3 char* lds = (LAS3 char*)smem;
;   LAS3 const float* tab = (LAS3 const float*)(lds + ATT_TAB);
;   const int hq_first = (MODE == 1) ? ((item0 >> 3) & 15) : 0;
.LBB0_836:
	v_writelane_b32 v255, s76, 56
	s_and_b64 vcc, exec, s[0:1]
	s_nop 0
	v_writelane_b32 v255, s77, 57
	s_cbranch_vccz .LBB0_901
	v_xor_b32_e32 v230, 32, v214
	v_lshlrev_b32_e32 v230, 2, v230
	v_mov_b32_e32 v2, v208
	s_load_dword s2, s[86:87], 0x0
	v_readlane_b32 s16, v254, 5
	v_readlane_b32 s17, v254, 6
	s_mov_b32 s0, s79
	s_mov_b32 s1, s17
	s_waitcnt lgkmcnt(0)
	v_cvt_f32_u32_e32 v113, s2
	s_cmp_lg_u64 s[0:1], 0
	v_readfirstlane_b32 s10, v2
	s_cbranch_scc0 .LBB0_903
	v_fmamk_f32 v0, 0, 0x4f800000, v113
	v_rcp_f32_e32 v0, v0
	s_sub_u32 s6, 0, s2
	s_subb_u32 s7, 0, 0
	v_mul_f32_e32 v0, 0x5f7ffffc, v0
	v_mul_f32_e32 v3, 0x2f800000, v0
	v_trunc_f32_e32 v3, v3
	v_fmac_f32_e32 v0, 0xcf800000, v3
	v_cvt_u32_f32_e32 v3, v3
	v_cvt_u32_f32_e32 v0, v0
	v_readfirstlane_b32 s8, v3
	v_readfirstlane_b32 s0, v0
	s_mul_i32 s1, s6, s8
	s_mul_hi_u32 s11, s6, s0
	s_mul_i32 s9, s7, s0
	s_add_i32 s1, s11, s1
	s_add_i32 s1, s1, s9
	s_mul_i32 s12, s6, s0
	s_mul_i32 s11, s0, s1
	s_mul_hi_u32 s13, s0, s12
	s_mul_hi_u32 s9, s0, s1
	s_add_u32 s11, s13, s11
	s_addc_u32 s9, 0, s9
	s_mul_hi_u32 s14, s8, s12
	s_mul_i32 s12, s8, s12
	s_add_u32 s11, s11, s12
	s_mul_hi_u32 s13, s8, s1
	s_addc_u32 s9, s9, s14
	s_addc_u32 s11, s13, 0
	s_mul_i32 s1, s8, s1
	s_add_u32 s1, s9, s1
	s_addc_u32 s9, 0, s11
	s_add_u32 s11, s0, s1
	s_cselect_b64 s[0:1], -1, 0
	s_cmp_lg_u64 s[0:1], 0
	s_addc_u32 s8, s8, s9
	s_mul_i32 s0, s6, s8
	s_mul_hi_u32 s1, s6, s11
	s_add_i32 s0, s1, s0
	s_mul_i32 s7, s7, s11
	s_add_i32 s0, s0, s7
	s_mul_i32 s6, s6, s11
	s_mul_hi_u32 s7, s8, s6
	s_mul_i32 s9, s8, s6
	s_mul_i32 s13, s11, s0
	s_mul_hi_u32 s6, s11, s6
	s_mul_hi_u32 s12, s11, s0
	s_add_u32 s6, s6, s13
	s_addc_u32 s12, 0, s12
	s_add_u32 s6, s6, s9
	s_mul_hi_u32 s1, s8, s0
	s_addc_u32 s6, s12, s7
	s_addc_u32 s1, s1, 0
	s_mul_i32 s0, s8, s0
	s_add_u32 s0, s6, s0
	s_addc_u32 s6, 0, s1
	s_add_u32 s7, s11, s0
	s_cselect_b64 s[0:1], -1, 0
	s_cmp_lg_u64 s[0:1], 0
	s_addc_u32 s0, s8, s6
	s_mul_i32 s6, s16, s0
	s_mul_hi_u32 s8, s16, s7
	s_mul_hi_u32 s1, s16, s0
	s_add_u32 s6, s8, s6
	s_addc_u32 s1, 0, s1
	s_mul_hi_u32 s9, s17, s7
	s_mul_i32 s7, s17, s7
	s_add_u32 s6, s6, s7
	s_mul_hi_u32 s8, s17, s0
	s_addc_u32 s1, s1, s9
	s_addc_u32 s6, s8, 0
	s_mul_i32 s0, s17, s0
	s_add_u32 s7, s1, s0
	s_addc_u32 s0, 0, s6
	s_mul_i32 s0, s2, s0
	s_mul_hi_u32 s1, s2, s7
	s_add_u32 s6, s7, 1
	s_add_u32 s8, s7, 2
	s_add_i32 s9, s1, s0
	s_mul_i32 s0, s2, s7
	s_sub_u32 s11, s16, s0
	s_cselect_b64 s[0:1], -1, 0
	s_cmp_lg_u64 s[0:1], 0
	s_subb_u32 s9, s17, s9
	s_sub_u32 s12, s11, s2
	s_cselect_b64 s[0:1], -1, 0
	s_cmp_lg_u64 s[0:1], 0
	s_subb_u32 s0, s9, 0
	s_cmp_ge_u32 s12, s2
	s_cselect_b32 s1, -1, 0
	s_cmp_eq_u32 s0, 0
	s_cselect_b32 s0, s1, -1
	s_cmp_lg_u32 s0, 0
	s_cselect_b32 s0, s8, s6
	s_cmp_ge_u32 s11, s2
	s_cselect_b32 s1, -1, 0
	s_cmp_eq_u32 s9, 0
	s_cselect_b32 s1, s1, -1
	s_cmp_lg_u32 s1, 0
	s_cselect_b32 s6, s0, s7
	v_cvt_f32_u32_e32 v132, s2
	s_cbranch_execnz .LBB0_840

; #define LAS3 __attribute__((address_space(3)))
; DI unsigned pk2(float lo, float hi) { f32x2 v = {lo, hi}; return __builtin_bit_cast(unsigned, __builtin_convertvector(v, bf16x2v)); }
; DI int swz(int row) { return (((row >> 1) & 1) << 2) | ((row >> 2) & 3); }
; template <int MODE>
; DI void attn_seq(const Params& p, int layer, char* smem, const int tid, const int nitems, bf16_t* ob, const int ostride) {
;     ...
;     float lsum = st.l + __shfl_xor(st.l, 32);
;     if (isA) lsum += __builtin_amdgcn_exp2f(p.a_sink[jl * 16 + hq] * LOG2E - st.m);
;     const float inv = 1.f / lsum;
;     LAS3 char* scr = lds + ATT_GATE + wv * 4096;
;     u32x4 gv0, gv1, gv2, gv3;
;     gv0 = *(LAS3 const u32x4*)(scr + 0 * 1024 + lane * 16); gv1 = *(LAS3 const u32x4*)(scr + 1 * 1024 + lane * 16);
;     gv2 = *(LAS3 const u32x4*)(scr + 2 * 1024 + lane * 16); gv3 = *(LAS3 const u32x4*)(scr + 3 * 1024 + lane * 16);
;     asm volatile("s_waitcnt lgkmcnt(0)" ::: "memory");
;     {
;       const int swr = swz(r & 15);
; #pragma unroll
;       for (int g4 = 0; g4 < 4; ++g4) {
;         u32x2 w0, w1;
;         w0[0] = pk2(st.o0[4 * g4 + 0] * inv, st.o0[4 * g4 + 1] * inv); w0[1] = pk2(st.o0[4 * g4 + 2] * inv, st.o0[4 * g4 + 3] * inv);
;         w1[0] = pk2(st.o1[4 * g4 + 0] * inv, st.o1[4 * g4 + 1] * inv); w1[1] = pk2(st.o1[4 * g4 + 2] * inv, st.o1[4 * g4 + 3] * inv);
;         *(LAS3 u32x2*)(scr + r * 128 + ((g4 ^ swr) * 16) + 8 * h) = w0;
;         *(LAS3 u32x2*)(scr + r * 128 + (((4 + g4) ^ swr) * 16) + 8 * h) = w1;
;       }
;     }
; #pragma unroll
;     for (int pass = 0; pass < 4; ++pass) {
;       const int row = (lane >> 3) + 8 * pass, piece = lane & 7;
;       const u32x4 ov = *(LAS3 const u32x4*)(scr + row * 128 + ((piece ^ swz(row & 15)) * 16));
.Lm0_noprefetch:
	s_or_b32 s0, s11, s88
	s_ashr_i32 s1, s0, 31
	v_readlane_b32 s16, v255, 36
	s_lshl_b64 s[0:1], s[0:1], 2
	v_readlane_b32 s20, v255, 40
	v_and_b32_e32 v2, 64, v214
	v_readlane_b32 s21, v255, 41
	s_add_u32 s0, s20, s0
	v_xor_b32_e32 v0, 32, v214
	v_add_u32_e32 v2, 64, v2
	s_addc_u32 s1, s21, s1
	v_cmp_lt_i32_e32 vcc, v0, v2
	s_mov_b32 s0, 0x3fb8aa3b
	s_nop 0
	v_cndmask_b32_e32 v0, v214, v0, vcc
	v_lshlrev_b32_e32 v0, 2, v0
	ds_bpermute_b32 v0, v0, v171
	s_lshl_b32 s78, s10, 1
	s_add_i32 s96, s96, 1
	s_cmp_ge_i32 s96, s7
	v_readlane_b32 s17, v255, 37
	s_waitcnt lgkmcnt(0)
	v_add_f32_e32 v0, v171, v0
	v_readlane_b32 s18, v255, 38
	v_readlane_b32 s19, v255, 39
	v_readlane_b32 s22, v255, 42
	v_readlane_b32 s23, v255, 43
	s_nop 0
	v_fma_f32 v2, v183, s0, -v117
	v_exp_f32_e32 v2, v2
	s_nop 0
	v_add_f32_e32 v0, v0, v2
	v_div_scale_f32 v2, s[0:1], v0, v0, 1.0
	v_rcp_f32_e32 v3, v2
	s_nop 0
	v_fma_f32 v4, -v2, v3, 1.0
	v_fmac_f32_e32 v3, v4, v3
	v_div_scale_f32 v4, vcc, 1.0, v0, 1.0
	v_mul_f32_e32 v5, v4, v3
	v_fma_f32 v6, -v2, v5, v4
	v_fmac_f32_e32 v5, v6, v3
	v_fma_f32 v2, -v2, v5, v4
	v_div_fmas_f32 v2, v2, v3, v5
	v_div_fixup_f32 v0, v2, v0, 1.0
	v_pk_mul_f32 v[14:15], v[32:33], v[0:1] op_sel_hi:[1,0]
	v_pk_mul_f32 v[32:33], v[34:35], v[0:1] op_sel_hi:[1,0]
	v_pk_mul_f32 v[16:17], v[16:17], v[0:1] op_sel_hi:[1,0]
	v_pk_mul_f32 v[18:19], v[18:19], v[0:1] op_sel_hi:[1,0]
	v_cvt_pk_bf16_f32 v14, v14, v15
	v_cvt_pk_bf16_f32 v15, v32, v33
	v_cvt_pk_bf16_f32 v16, v16, v17
	v_cvt_pk_bf16_f32 v17, v18, v19
	v_add_u32_e32 v18, v153, v154
	ds_read_b128 v[48:51], v158
	ds_read_b128 v[10:13], v158 offset:1024
	ds_read_b128 v[6:9], v158 offset:2048
	ds_read_b128 v[2:5], v158 offset:3072
	s_waitcnt lgkmcnt(0)
	ds_write_b64 v18, v[14:15]
	ds_write_b64 v159, v[16:17]
	v_pk_mul_f32 v[14:15], v[36:37], v[0:1] op_sel_hi:[1,0]
	v_pk_mul_f32 v[16:17], v[38:39], v[0:1] op_sel_hi:[1,0]
	v_cvt_pk_bf16_f32 v14, v14, v15
	v_cvt_pk_bf16_f32 v15, v16, v17
	v_pk_mul_f32 v[16:17], v[20:21], v[0:1] op_sel_hi:[1,0]
	v_pk_mul_f32 v[18:19], v[22:23], v[0:1] op_sel_hi:[1,0]
	v_cvt_pk_bf16_f32 v16, v16, v17
	v_cvt_pk_bf16_f32 v17, v18, v19
	ds_write_b64 v160, v[14:15]
	ds_write_b64 v161, v[16:17]
	v_pk_mul_f32 v[14:15], v[40:41], v[0:1] op_sel_hi:[1,0]
	v_pk_mul_f32 v[16:17], v[42:43], v[0:1] op_sel_hi:[1,0]
	v_cvt_pk_bf16_f32 v14, v14, v15
	v_cvt_pk_bf16_f32 v15, v16, v17
	v_pk_mul_f32 v[16:17], v[24:25], v[0:1] op_sel_hi:[1,0]
	v_pk_mul_f32 v[18:19], v[26:27], v[0:1] op_sel_hi:[1,0]
	v_cvt_pk_bf16_f32 v16, v16, v17
	v_cvt_pk_bf16_f32 v17, v18, v19
	ds_write_b64 v162, v[14:15]
	ds_write_b64 v163, v[16:17]
	v_pk_mul_f32 v[14:15], v[44:45], v[0:1] op_sel_hi:[1,0]
	v_pk_mul_f32 v[16:17], v[46:47], v[0:1] op_sel_hi:[1,0]
	v_cvt_pk_bf16_f32 v14, v14, v15
	v_cvt_pk_bf16_f32 v15, v16, v17
	v_pk_mul_f32 v[16:17], v[28:29], v[0:1] op_sel_hi:[1,0]
	v_pk_mul_f32 v[18:19], v[30:31], v[0:1] op_sel_hi:[1,0]
	v_cvt_pk_bf16_f32 v16, v16, v17
	v_cvt_pk_bf16_f32 v17, v18, v19
	ds_write_b64 v164, v[14:15]
	ds_write_b64 v165, v[16:17]
	ds_read_b128 v[14:17], v166
	s_waitcnt lgkmcnt(12)
	v_lshlrev_b32_e32 v22, 16, v48
	v_and_b32_e32 v23, 0xffff0000, v48
	v_lshl_add_u64 v[18:19], v[114:115], 0, s[78:79]
	v_or_b32_e32 v0, s13, v155
	s_waitcnt lgkmcnt(0)
; #define LAS3 __attribute__((address_space(3)))
; DI unsigned pk2(float lo, float hi) { f32x2 v = {lo, hi}; return __builtin_bit_cast(unsigned, __builtin_convertvector(v, bf16x2v)); }
; DI float bflo(unsigned u) { return __uint_as_float(u << 16); }
; DI float bfhi(unsigned u) { return __uint_as_float(u & 0xffff0000u); }
; DI int swz(int row) { return (((row >> 1) & 1) << 2) | ((row >> 2) & 3); }
; template <int MODE>
; DI void attn_seq(const Params& p, int layer, char* smem, const int tid, const int nitems, bf16_t* ob, const int ostride) {
;     ...
; #pragma unroll
;     for (int pass = 0; pass < 4; ++pass) {
;       const int row = (lane >> 3) + 8 * pass, piece = lane & 7;
;       const u32x4 ov = *(LAS3 const u32x4*)(scr + row * 128 + ((piece ^ swz(row & 15)) * 16));
;       int tqr;
;       if (MODE == 0) tqr = d.b * 2048 + q0i + row;
;       else if (MODE == 1) tqr = d.b * 2048 + ((item & 7) * 4 + 2 * (wv >> 2) + (row >> 4)) * 64 + 16 * (wv & 3) + (row & 15);
;       else if (MODE == 2) tqr = TL + d.b * 256 + (item & 3) * 64 + 32 * (wv >> 2) + row;
;       else tqr = TL + d.b * 256 + wv * 32 + row;
;       const u32x4 gv = (pass == 0) ? gv0 : (pass == 1) ? gv1 : (pass == 2) ? gv2 : gv3;
;       uint4 w;
;       w.x = pk2(bflo(ov[0]) * bflo(gv[0]), bfhi(ov[0]) * bfhi(gv[0]));
;       w.y = pk2(bflo(ov[1]) * bflo(gv[1]), bfhi(ov[1]) * bfhi(gv[1]));
;       w.z = pk2(bflo(ov[2]) * bflo(gv[2]), bfhi(ov[2]) * bfhi(gv[2]));
;       w.w = pk2(bflo(ov[3]) * bflo(gv[3]), bfhi(ov[3]) * bfhi(gv[3]));
;       *(uint4*)(ob + (size_t)tqr * ostride + hq * 64 + piece * 8) = w;
;     }
;     asm volatile("s_waitcnt lgkmcnt(0)" ::: "memory");
	v_lshlrev_b32_e32 v20, 16, v14
	v_and_b32_e32 v21, 0xffff0000, v14
	v_pk_mul_f32 v[20:21], v[22:23], v[20:21]
	v_lshlrev_b32_e32 v22, 16, v49
	v_cvt_pk_bf16_f32 v14, v20, v21
	v_lshlrev_b32_e32 v20, 16, v15
	v_and_b32_e32 v21, 0xffff0000, v15
	v_and_b32_e32 v23, 0xffff0000, v49
	v_pk_mul_f32 v[20:21], v[22:23], v[20:21]
	v_lshlrev_b32_e32 v22, 16, v50
	v_cvt_pk_bf16_f32 v15, v20, v21
	v_lshlrev_b32_e32 v20, 16, v16
	v_and_b32_e32 v21, 0xffff0000, v16
	v_and_b32_e32 v23, 0xffff0000, v50
	v_pk_mul_f32 v[20:21], v[22:23], v[20:21]
	v_lshlrev_b32_e32 v22, 16, v51
	v_cvt_pk_bf16_f32 v16, v20, v21
	v_lshlrev_b32_e32 v20, 16, v17
	v_and_b32_e32 v21, 0xffff0000, v17
	v_and_b32_e32 v23, 0xffff0000, v51
	v_pk_mul_f32 v[20:21], v[22:23], v[20:21]
	v_lshlrev_b32_e32 v22, 16, v10
	v_cvt_pk_bf16_f32 v17, v20, v21
	v_lshl_add_u64 v[20:21], v[18:19], 0, v[120:121]
	global_store_dwordx4 v[20:21], v[14:17], off
	ds_read_b128 v[14:17], v167
	v_and_b32_e32 v23, 0xffff0000, v10
	s_waitcnt lgkmcnt(0)
	v_lshlrev_b32_e32 v20, 16, v14
	v_and_b32_e32 v21, 0xffff0000, v14
	v_pk_mul_f32 v[20:21], v[22:23], v[20:21]
	v_lshlrev_b32_e32 v14, 16, v15
	v_cvt_pk_bf16_f32 v10, v20, v21
	v_and_b32_e32 v15, 0xffff0000, v15
	v_lshlrev_b32_e32 v20, 16, v11
	v_and_b32_e32 v21, 0xffff0000, v11
	v_pk_mul_f32 v[14:15], v[20:21], v[14:15]
	v_lshlrev_b32_e32 v20, 16, v12
	v_cvt_pk_bf16_f32 v11, v14, v15
	v_lshlrev_b32_e32 v14, 16, v16
	v_and_b32_e32 v15, 0xffff0000, v16
	v_and_b32_e32 v21, 0xffff0000, v12
	v_pk_mul_f32 v[14:15], v[20:21], v[14:15]
	v_lshlrev_b32_e32 v16, 16, v13
	v_cvt_pk_bf16_f32 v12, v14, v15
	v_lshlrev_b32_e32 v14, 16, v17
	v_and_b32_e32 v15, 0xffff0000, v17
	v_and_b32_e32 v17, 0xffff0000, v13
	v_pk_mul_f32 v[14:15], v[16:17], v[14:15]
	v_lshlrev_b32_e32 v16, 16, v6
	v_cvt_pk_bf16_f32 v13, v14, v15
	v_mad_i64_i32 v[14:15], s[0:1], v0, s92, v[18:19]
	global_store_dwordx4 v[14:15], v[10:13], off
	ds_read_b128 v[10:13], v168
	v_and_b32_e32 v17, 0xffff0000, v6
	v_or_b32_e32 v0, s13, v156
	s_waitcnt lgkmcnt(0)
	v_lshlrev_b32_e32 v14, 16, v10
	v_and_b32_e32 v15, 0xffff0000, v10
	v_pk_mul_f32 v[14:15], v[16:17], v[14:15]
	v_lshlrev_b32_e32 v10, 16, v11
	v_cvt_pk_bf16_f32 v6, v14, v15
	v_and_b32_e32 v11, 0xffff0000, v11
	v_lshlrev_b32_e32 v14, 16, v7
	v_and_b32_e32 v15, 0xffff0000, v7
	v_pk_mul_f32 v[10:11], v[14:15], v[10:11]
	v_lshlrev_b32_e32 v14, 16, v8
	v_cvt_pk_bf16_f32 v7, v10, v11
	v_lshlrev_b32_e32 v10, 16, v12
	v_and_b32_e32 v11, 0xffff0000, v12
	v_and_b32_e32 v15, 0xffff0000, v8
	v_pk_mul_f32 v[10:11], v[14:15], v[10:11]
	v_lshlrev_b32_e32 v12, 16, v9
	v_cvt_pk_bf16_f32 v8, v10, v11
	v_lshlrev_b32_e32 v10, 16, v13
	v_and_b32_e32 v11, 0xffff0000, v13
	v_and_b32_e32 v13, 0xffff0000, v9
	v_pk_mul_f32 v[10:11], v[12:13], v[10:11]
	v_lshlrev_b32_e32 v12, 16, v2
	v_cvt_pk_bf16_f32 v9, v10, v11
	v_mad_i64_i32 v[10:11], s[0:1], v0, s92, v[18:19]
	global_store_dwordx4 v[10:11], v[6:9], off
	ds_read_b128 v[6:9], v169
	v_and_b32_e32 v13, 0xffff0000, v2
	v_or_b32_e32 v0, s13, v157
	s_waitcnt lgkmcnt(0)
	v_lshlrev_b32_e32 v10, 16, v6
	v_and_b32_e32 v11, 0xffff0000, v6
	v_pk_mul_f32 v[10:11], v[12:13], v[10:11]
	v_lshlrev_b32_e32 v6, 16, v7
	v_cvt_pk_bf16_f32 v2, v10, v11
	v_and_b32_e32 v7, 0xffff0000, v7
	v_lshlrev_b32_e32 v10, 16, v3
	v_and_b32_e32 v11, 0xffff0000, v3
	v_pk_mul_f32 v[6:7], v[10:11], v[6:7]
	v_lshlrev_b32_e32 v10, 16, v4
	v_cvt_pk_bf16_f32 v3, v6, v7
	v_lshlrev_b32_e32 v6, 16, v8
	v_and_b32_e32 v7, 0xffff0000, v8
	v_and_b32_e32 v11, 0xffff0000, v4
	v_pk_mul_f32 v[6:7], v[10:11], v[6:7]
	v_lshlrev_b32_e32 v8, 16, v5
	v_cvt_pk_bf16_f32 v4, v6, v7
	v_lshlrev_b32_e32 v6, 16, v9
	v_and_b32_e32 v7, 0xffff0000, v9
	v_and_b32_e32 v9, 0xffff0000, v5
	v_pk_mul_f32 v[6:7], v[8:9], v[6:7]
	s_nop 0
	v_cvt_pk_bf16_f32 v5, v6, v7
	v_mad_i64_i32 v[6:7], s[0:1], v0, s92, v[18:19]
	global_store_dwordx4 v[6:7], v[2:5], off
	s_waitcnt lgkmcnt(0)
	s_cbranch_scc1 .LBB0_875

; #define LAS3 __attribute__((address_space(3)))
; DI unsigned pk2(float lo, float hi) { f32x2 v = {lo, hi}; return __builtin_bit_cast(unsigned, __builtin_convertvector(v, bf16x2v)); }
; DI void pv_tile(LAS3 const char* vb, const AttnLane& L, const f32x16& pr, f32x16& o0, f32x16& o1) {
;   u32x4 w0, w1;
;   w0[0] = pk2(pr[0], pr[1]); w0[1] = pk2(pr[2], pr[3]); w0[2] = pk2(pr[4], pr[5]); w0[3] = pk2(pr[6], pr[7]);
;   w1[0] = pk2(pr[8], pr[9]); w1[1] = pk2(pr[10], pr[11]); w1[2] = pk2(pr[12], pr[13]); w1[3] = pk2(pr[14], pr[15]);
;   const bf16x8 pf0 = __builtin_bit_cast(bf16x8, w0), pf1 = __builtin_bit_cast(bf16x8, w1);
;   o0 = __builtin_amdgcn_mfma_f32_32x32x16_bf16(tr_pair(vb + L.vr00, vb + L.vr01), pf0, o0, 0, 0, 0);
;   o1 = __builtin_amdgcn_mfma_f32_32x32x16_bf16(tr_pair(vb + L.vr10, vb + L.vr11), pf0, o1, 0, 0, 0);
;   o0 = __builtin_amdgcn_mfma_f32_32x32x16_bf16(tr_pair(vb + 2048 + L.vr00, vb + 2048 + L.vr01), pf1, o0, 0, 0, 0);
;   o1 = __builtin_amdgcn_mfma_f32_32x32x16_bf16(tr_pair(vb + 2048 + L.vr10, vb + 2048 + L.vr11), pf1, o1, 0, 0, 0);
; }
; template <int MK> ...
;     ...
; #pragma unroll
;   for (int v = 0; v < 16; ++v) s0[v] = __builtin_amdgcn_exp2f(s0[v]);
;   const float a0 = (s0[0] + s0[1]) + (s0[2] + s0[3]), a1 = (s0[4] + s0[5]) + (s0[6] + s0[7]);
;   const float a2 = (s0[8] + s0[9]) + (s0[10] + s0[11]), a3 = (s0[12] + s0[13]) + (s0[14] + s0[15]);
;   pv_tile(v0, L, s0, st.o0, st.o1);
; #pragma unroll
;   for (int v = 0; v < 16; ++v) s1[v] = __builtin_amdgcn_exp2f(s1[v]);
;   const float a4 = (s1[0] + s1[1]) + (s1[2] + s1[3]), a5 = (s1[4] + s1[5]) + (s1[6] + s1[7]);
;   const float a6 = (s1[8] + s1[9]) + (s1[10] + s1[11]), a7 = (s1[12] + s1[13]) + (s1[14] + s1[15]);
;   pv_tile(v1, L, s1, st.o0, st.o1);
;   const float sum = ((a0 + a1) + (a2 + a3)) + ((a4 + a5) + (a6 + a7));
;   st.l += sum;
;   const float tot = sum + __shfl_xor(sum, 32);
;   if (__builtin_amdgcn_ballot_w64(tot > 256.f) != 0) {
;     const float delta = fmaxf(__builtin_amdgcn_logf(tot), 0.f);
;     const float alpha = __builtin_amdgcn_exp2f(-delta);
;     st.m += delta; st.l *= alpha;
; #pragma unroll
;     for (int v = 0; v < 16; ++v) { st.cinit[v] -= delta; st.o0[v] *= alpha; st.o1[v] *= alpha; }
;   }
.LBB0_872:
	v_add_u32_e32 v0, s33, v149
	v_exp_f32_e32 v125, v80
	v_exp_f32_e32 v129, v81
	v_exp_f32_e32 v127, v82
	v_exp_f32_e32 v131, v83
	v_exp_f32_e32 v83, v84
	v_exp_f32_e32 v123, v85
	v_exp_f32_e32 v85, v86
	v_exp_f32_e32 v87, v87
	v_exp_f32_e32 v3, v88
	v_exp_f32_e32 v7, v89
	v_exp_f32_e32 v5, v90
	v_exp_f32_e32 v11, v91
	v_add_u32_e32 v180, s33, v150
	s_nop 0
	ds_read_b64_tr_b16 v[88:89], v0 offset:16384
	ds_read_b64_tr_b16 v[90:91], v180 offset:16384
	v_add_u32_e32 v181, s33, v151
	v_exp_f32_e32 v124, v64
	v_exp_f32_e32 v128, v65
	v_exp_f32_e32 v126, v66
	v_exp_f32_e32 v130, v67
	v_cvt_pk_bf16_f32 v64, v125, v129
	v_cvt_pk_bf16_f32 v65, v127, v131
	v_cvt_pk_bf16_f32 v66, v83, v123
	v_cvt_pk_bf16_f32 v67, v85, v87
	v_exp_f32_e32 v9, v92
	v_exp_f32_e32 v15, v93
	v_exp_f32_e32 v13, v94
	v_exp_f32_e32 v81, v95
	v_add_u32_e32 v182, s33, v152
	ds_read_b64_tr_b16 v[92:93], v181 offset:16384
	ds_read_b64_tr_b16 v[94:95], v182 offset:16384
	ds_read_b64_tr_b16 v[172:173], v0 offset:18432
	ds_read_b64_tr_b16 v[174:175], v180 offset:18432
	ds_read_b64_tr_b16 v[176:177], v181 offset:18432
	ds_read_b64_tr_b16 v[178:179], v182 offset:18432
	s_waitcnt lgkmcnt(6)
	v_mfma_f32_32x32x16_bf16 v[32:47], v[88:91], v[64:67], v[32:47]
	v_exp_f32_e32 v82, v68
	v_exp_f32_e32 v122, v69
	v_exp_f32_e32 v84, v70
	v_exp_f32_e32 v86, v71
	v_exp_f32_e32 v2, v72
	v_exp_f32_e32 v6, v73
	v_exp_f32_e32 v4, v74
	s_waitcnt lgkmcnt(4)
	v_mfma_f32_32x32x16_bf16 v[16:31], v[92:95], v[64:67], v[16:31]
	v_cvt_pk_bf16_f32 v64, v3, v7
	v_cvt_pk_bf16_f32 v65, v5, v11
	v_cvt_pk_bf16_f32 v66, v9, v15
	v_cvt_pk_bf16_f32 v67, v13, v81
	v_exp_f32_e32 v10, v75
	v_exp_f32_e32 v8, v76
	v_exp_f32_e32 v14, v77
	s_waitcnt lgkmcnt(2)
	v_mfma_f32_32x32x16_bf16 v[32:47], v[172:175], v[64:67], v[32:47]
	v_exp_f32_e32 v12, v78
	v_exp_f32_e32 v80, v79
	ds_read_b64_tr_b16 v[68:69], v0 offset:20480
	ds_read_b64_tr_b16 v[70:71], v180 offset:20480
	ds_read_b64_tr_b16 v[72:73], v181 offset:20480
	ds_read_b64_tr_b16 v[74:75], v182 offset:20480
	ds_read_b64_tr_b16 v[76:77], v0 offset:22528
	ds_read_b64_tr_b16 v[78:79], v180 offset:22528
	ds_read_b64_tr_b16 v[88:89], v181 offset:22528
	ds_read_b64_tr_b16 v[90:91], v182 offset:22528
	v_add_f32_e32 v92, v124, v128
	v_add_f32_e32 v93, v125, v129
	v_add_f32_e32 v94, v126, v130
	v_add_f32_e32 v95, v127, v131
	s_waitcnt lgkmcnt(8)
	v_mfma_f32_32x32x16_bf16 v[16:31], v[176:179], v[64:67], v[16:31]
	v_cvt_pk_bf16_f32 v64, v124, v128
	v_cvt_pk_bf16_f32 v65, v126, v130
	v_cvt_pk_bf16_f32 v66, v82, v122
	v_cvt_pk_bf16_f32 v67, v84, v86
	s_waitcnt lgkmcnt(6)
	s_nop 0
	v_mfma_f32_32x32x16_bf16 v[32:47], v[68:71], v[64:67], v[32:47]
	v_add_f32_e64 v70, v82, v122
	v_add_f32_e64 v71, v83, v123
	v_add_f32_e64 v82, v84, v86
	v_add_f32_e64 v83, v85, v87
	v_add_f32_e64 v84, v4, v10
	v_add_f32_e64 v85, v5, v11
	v_add_f32_e32 v70, v70, v82
	v_add_f32_e32 v71, v71, v83
	v_add_f32_e32 v82, v2, v6
	v_add_f32_e32 v83, v3, v7
	v_add_f32_e32 v68, v92, v94
	v_add_f32_e32 v69, v93, v95
	v_add_f32_e32 v82, v82, v84
	v_add_f32_e32 v83, v83, v85
	s_waitcnt lgkmcnt(4)
	v_mfma_f32_32x32x16_bf16 v[16:31], v[72:75], v[64:67], v[16:31]
	v_add_f32_e64 v64, v8, v14
	v_add_f32_e64 v65, v9, v15
	v_add_f32_e64 v66, v12, v80
	v_add_f32_e64 v67, v13, v81
	v_cvt_pk_bf16_f32 v2, v2, v6
	v_add_f32_e32 v64, v64, v66
	v_add_f32_e32 v65, v65, v67
	v_cvt_pk_bf16_f32 v3, v4, v10
	v_cvt_pk_bf16_f32 v4, v8, v14
	v_add_f32_e32 v6, v68, v70
	v_add_f32_e32 v7, v69, v71
	v_add_f32_e32 v8, v82, v64
	v_add_f32_e32 v9, v83, v65
	v_cvt_pk_bf16_f32 v5, v12, v80
	v_add_f32_e32 v6, v6, v8
	v_add_f32_e32 v7, v7, v9
	s_nop 0
	v_add_f32_e32 v0, v6, v7
	s_waitcnt lgkmcnt(2)
	v_mfma_f32_32x32x16_bf16 v[32:47], v[76:79], v[2:5], v[32:47]
	v_add_f32_e32 v171, v171, v0
	ds_bpermute_b32 v6, v230, v0
	s_waitcnt lgkmcnt(0)
	v_add_f32_e32 v0, v0, v6
	v_mfma_f32_32x32x16_bf16 v[16:31], v[88:91], v[2:5], v[16:31]
	v_cmp_lt_f32_e32 vcc, s68, v0
	s_cbranch_vccz .LBB0_865
	v_log_f32_e32 v0, v0
	s_nop 0
	v_max_f32_e32 v2, 0, v0
	v_exp_f32_e64 v0, -v2
	v_add_f32_e32 v117, v117, v2
	v_sub_f32_e32 v63, v63, v2
	v_sub_f32_e32 v62, v62, v2
	v_sub_f32_e32 v61, v61, v2
	v_sub_f32_e32 v60, v60, v2
	v_sub_f32_e32 v59, v59, v2
	v_mul_f32_e32 v171, v171, v0
	v_sub_f32_e32 v58, v58, v2
	v_sub_f32_e32 v57, v57, v2
	v_sub_f32_e32 v56, v56, v2
	v_sub_f32_e32 v55, v55, v2
	v_sub_f32_e32 v54, v54, v2
	v_sub_f32_e32 v53, v53, v2
	v_sub_f32_e32 v52, v52, v2
	v_sub_f32_e32 v51, v51, v2
	v_sub_f32_e32 v50, v50, v2
	v_sub_f32_e32 v49, v49, v2
	v_sub_f32_e32 v48, v48, v2
	v_pk_mul_f32 v[46:47], v[46:47], v[0:1] op_sel_hi:[1,0]
	v_pk_mul_f32 v[44:45], v[44:45], v[0:1] op_sel_hi:[1,0]
	v_pk_mul_f32 v[42:43], v[42:43], v[0:1] op_sel_hi:[1,0]
	v_pk_mul_f32 v[40:41], v[40:41], v[0:1] op_sel_hi:[1,0]
	v_pk_mul_f32 v[38:39], v[38:39], v[0:1] op_sel_hi:[1,0]
	v_pk_mul_f32 v[36:37], v[36:37], v[0:1] op_sel_hi:[1,0]
	v_pk_mul_f32 v[34:35], v[34:35], v[0:1] op_sel_hi:[1,0]
	v_pk_mul_f32 v[32:33], v[32:33], v[0:1] op_sel_hi:[1,0]
	v_pk_mul_f32 v[30:31], v[30:31], v[0:1] op_sel_hi:[1,0]
	v_pk_mul_f32 v[28:29], v[28:29], v[0:1] op_sel_hi:[1,0]
	v_pk_mul_f32 v[26:27], v[26:27], v[0:1] op_sel_hi:[1,0]
	v_pk_mul_f32 v[24:25], v[24:25], v[0:1] op_sel_hi:[1,0]
	v_pk_mul_f32 v[22:23], v[22:23], v[0:1] op_sel_hi:[1,0]
	v_pk_mul_f32 v[20:21], v[20:21], v[0:1] op_sel_hi:[1,0]
	v_pk_mul_f32 v[18:19], v[18:19], v[0:1] op_sel_hi:[1,0]
	v_pk_mul_f32 v[16:17], v[16:17], v[0:1] op_sel_hi:[1,0]
	s_branch .LBB0_865
